# nt on the memory-K/V projection GEMM's weight-operand DMA loads (each weight tile is read once per XCD)
# baseline (speedup 1.0000x reference)
.LBB0_83:
	s_add_u32 s10, s8, 0xfffc0080
	s_addc_u32 s11, s9, -1
	s_add_i32 s40, 0, 0x10000
	s_cmp_eq_u32 vcc_hi, 12
	s_cselect_b32 s53, s27, s11
	s_cselect_b32 s52, s89, s10
	s_cselect_b32 s11, s19, vcc_lo
	s_cselect_b32 s10, s90, s97
	s_add_i32 s25, 0, 0x14000
	v_add_u32_e32 v144, s40, v159
	v_add_u32_e32 v158, s25, v159
	ds_read_b128 v[132:135], v144
	ds_read_b128 v[136:139], v144 offset:1024
	ds_read_b128 v[140:143], v144 offset:2048
	ds_read_b128 v[144:147], v144 offset:3072
	ds_read_b128 v[190:193], v158
	ds_read_b128 v[194:197], v158 offset:1024
	ds_read_b128 v[198:201], v158 offset:2048
	ds_read_b128 v[202:205], v158 offset:3072
	v_lshl_add_u64 v[174:175], s[8:9], 0, v[154:155]
	s_add_i32 m0, s49, 0xc000
	ds_read_b128 v[206:209], v179
	ds_read_b128 v[228:231], v179 offset:1024
	ds_read_b128 v[232:235], v179 offset:2048
	ds_read_b128 v[236:239], v179 offset:3072
	ds_read_b128 v[240:243], v179 offset:4096
	ds_read_b128 v[244:247], v179 offset:5120
	ds_read_b128 v[224:227], v179 offset:6144
	ds_read_b128 v[218:221], v179 offset:7168
	global_load_lds_dwordx4 v[174:175], off
	v_lshl_add_u64 v[174:175], s[8:9], 0, v[156:157]
	s_add_i32 m0, s49, 0xe000
	s_nop 0
	global_load_lds_dwordx4 v[174:175], off
	s_waitcnt vmcnt(8)
	s_waitcnt lgkmcnt(0)
	s_barrier
	s_setprio 1
	s_waitcnt lgkmcnt(0)
	v_mfma_f32_16x16x32_bf16 v[128:131], v[132:135], v[206:209], v[128:131]
	v_mfma_f32_16x16x32_bf16 v[124:127], v[140:143], v[206:209], v[124:127]
	v_mfma_f32_16x16x32_bf16 v[112:115], v[132:135], v[232:235], v[112:115]
	v_mfma_f32_16x16x32_bf16 v[108:111], v[140:143], v[232:235], v[108:111]
	v_mfma_f32_16x16x32_bf16 v[96:99], v[132:135], v[240:243], v[96:99]
	v_mfma_f32_16x16x32_bf16 v[92:95], v[140:143], v[240:243], v[92:95]
	v_mfma_f32_16x16x32_bf16 v[80:83], v[132:135], v[224:227], v[80:83]
	v_mfma_f32_16x16x32_bf16 v[76:79], v[140:143], v[224:227], v[76:79]
	v_mfma_f32_16x16x32_bf16 v[128:131], v[136:139], v[228:231], v[128:131]
	v_mfma_f32_16x16x32_bf16 v[124:127], v[144:147], v[228:231], v[124:127]
	v_mfma_f32_16x16x32_bf16 v[112:115], v[136:139], v[236:239], v[112:115]
	v_mfma_f32_16x16x32_bf16 v[108:111], v[144:147], v[236:239], v[108:111]
	v_mfma_f32_16x16x32_bf16 v[96:99], v[136:139], v[244:247], v[96:99]
	v_mfma_f32_16x16x32_bf16 v[92:95], v[144:147], v[244:247], v[92:95]
	v_mfma_f32_16x16x32_bf16 v[80:83], v[136:139], v[218:221], v[80:83]
	v_mfma_f32_16x16x32_bf16 v[76:79], v[144:147], v[218:221], v[76:79]
	s_setprio 0
	s_setprio 1
	v_mfma_f32_16x16x32_bf16 v[120:123], v[190:193], v[206:209], v[120:123]
	v_mfma_f32_16x16x32_bf16 v[116:119], v[198:201], v[206:209], v[116:119]
	v_mfma_f32_16x16x32_bf16 v[104:107], v[190:193], v[232:235], v[104:107]
	v_mfma_f32_16x16x32_bf16 v[100:103], v[198:201], v[232:235], v[100:103]
	v_mfma_f32_16x16x32_bf16 v[88:91], v[190:193], v[240:243], v[88:91]
	v_mfma_f32_16x16x32_bf16 v[84:87], v[198:201], v[240:243], v[84:87]
	v_mfma_f32_16x16x32_bf16 v[72:75], v[190:193], v[224:227], v[72:75]
	v_mfma_f32_16x16x32_bf16 v[68:71], v[198:201], v[224:227], v[68:71]
	v_mfma_f32_16x16x32_bf16 v[120:123], v[194:197], v[228:231], v[120:123]
	v_mfma_f32_16x16x32_bf16 v[116:119], v[202:205], v[228:231], v[116:119]
	v_mfma_f32_16x16x32_bf16 v[104:107], v[194:197], v[236:239], v[104:107]
	v_mfma_f32_16x16x32_bf16 v[100:103], v[202:205], v[236:239], v[100:103]
	v_mfma_f32_16x16x32_bf16 v[88:91], v[194:197], v[244:247], v[88:91]
	v_mfma_f32_16x16x32_bf16 v[84:87], v[202:205], v[244:247], v[84:87]
	v_mfma_f32_16x16x32_bf16 v[72:75], v[194:197], v[218:221], v[72:75]
	v_mfma_f32_16x16x32_bf16 v[68:71], v[202:205], v[218:221], v[68:71]
	s_setprio 0
	s_barrier
	s_add_i32 s40, s40, s55
	v_lshl_add_u64 v[174:175], s[10:11], 0, v[180:181]
	s_mov_b32 m0, s40
	ds_read_b128 v[206:209], v179 offset:16384
	ds_read_b128 v[218:221], v179 offset:17408
	ds_read_b128 v[224:227], v179 offset:18432
	ds_read_b128 v[228:231], v179 offset:19456
	ds_read_b128 v[232:235], v179 offset:20480
	ds_read_b128 v[236:239], v179 offset:21504
	ds_read_b128 v[240:243], v179 offset:22528
	ds_read_b128 v[244:247], v179 offset:23552
	global_load_lds_dwordx4 v[174:175], off nt
	s_add_i32 m0, s40, 0x2000
	s_add_u32 s40, s10, 0x40000
	v_lshl_add_u64 v[210:211], s[10:11], 0, v[150:151]
	s_addc_u32 s41, s11, 0
	s_add_i32 s25, s25, s55
	global_load_lds_dwordx4 v[210:211], off nt
	v_lshl_add_u64 v[248:249], s[40:41], 0, v[180:181]
	s_mov_b32 m0, s25
	v_lshl_add_u64 v[182:183], s[52:53], 0, v[148:149]
	global_load_lds_dwordx4 v[248:249], off nt
	v_lshl_add_u64 v[248:249], s[40:41], 0, v[150:151]
	s_add_i32 m0, s25, 0x2000
	s_nop 0
	global_load_lds_dwordx4 v[248:249], off nt
	v_lshl_add_u64 v[248:249], s[52:53], 0, v[0:1]
	s_mov_b32 m0, s49
	s_nop 0
	global_load_lds_dwordx4 v[248:249], off
	s_mov_b32 m0, s51
	s_nop 0
	global_load_lds_dwordx4 v[182:183], off
	s_waitcnt vmcnt(8)
	s_waitcnt lgkmcnt(0)
	s_barrier
	s_setprio 1
	s_waitcnt lgkmcnt(0)
	v_mfma_f32_16x16x32_bf16 v[64:67], v[132:135], v[206:209], v[64:67]
	v_mfma_f32_16x16x32_bf16 v[60:63], v[140:143], v[206:209], v[60:63]
	v_mfma_f32_16x16x32_bf16 v[48:51], v[132:135], v[224:227], v[48:51]
	v_mfma_f32_16x16x32_bf16 v[44:47], v[140:143], v[224:227], v[44:47]
	v_mfma_f32_16x16x32_bf16 v[32:35], v[132:135], v[232:235], v[32:35]
	v_mfma_f32_16x16x32_bf16 v[28:31], v[140:143], v[232:235], v[28:31]
	v_mfma_f32_16x16x32_bf16 v[16:19], v[132:135], v[240:243], v[16:19]
	v_mfma_f32_16x16x32_bf16 v[12:15], v[140:143], v[240:243], v[12:15]
	v_mfma_f32_16x16x32_bf16 v[64:67], v[136:139], v[218:221], v[64:67]
	v_mfma_f32_16x16x32_bf16 v[60:63], v[144:147], v[218:221], v[60:63]
	v_mfma_f32_16x16x32_bf16 v[48:51], v[136:139], v[228:231], v[48:51]
	v_mfma_f32_16x16x32_bf16 v[44:47], v[144:147], v[228:231], v[44:47]
	v_mfma_f32_16x16x32_bf16 v[32:35], v[136:139], v[236:239], v[32:35]
	v_mfma_f32_16x16x32_bf16 v[28:31], v[144:147], v[236:239], v[28:31]
	v_mfma_f32_16x16x32_bf16 v[16:19], v[136:139], v[244:247], v[16:19]
	v_mfma_f32_16x16x32_bf16 v[12:15], v[144:147], v[244:247], v[12:15]
	s_setprio 0
	s_setprio 1
	v_mfma_f32_16x16x32_bf16 v[56:59], v[190:193], v[206:209], v[56:59]
	v_mfma_f32_16x16x32_bf16 v[52:55], v[198:201], v[206:209], v[52:55]
	v_mfma_f32_16x16x32_bf16 v[40:43], v[190:193], v[224:227], v[40:43]
	v_mfma_f32_16x16x32_bf16 v[36:39], v[198:201], v[224:227], v[36:39]
	v_mfma_f32_16x16x32_bf16 v[24:27], v[190:193], v[232:235], v[24:27]
	v_mfma_f32_16x16x32_bf16 v[20:23], v[198:201], v[232:235], v[20:23]
	v_mfma_f32_16x16x32_bf16 v[8:11], v[190:193], v[240:243], v[8:11]
	v_mfma_f32_16x16x32_bf16 v[4:7], v[198:201], v[240:243], v[4:7]
	v_mfma_f32_16x16x32_bf16 v[56:59], v[194:197], v[218:221], v[56:59]
	v_mfma_f32_16x16x32_bf16 v[52:55], v[202:205], v[218:221], v[52:55]
	v_mfma_f32_16x16x32_bf16 v[40:43], v[194:197], v[228:231], v[40:43]
	v_mfma_f32_16x16x32_bf16 v[36:39], v[202:205], v[228:231], v[36:39]
	v_mfma_f32_16x16x32_bf16 v[24:27], v[194:197], v[236:239], v[24:27]
	v_mfma_f32_16x16x32_bf16 v[20:23], v[202:205], v[236:239], v[20:23]
	v_mfma_f32_16x16x32_bf16 v[8:11], v[194:197], v[244:247], v[8:11]
	v_mfma_f32_16x16x32_bf16 v[4:7], v[202:205], v[244:247], v[4:7]
	s_setprio 0
	s_barrier
	s_add_i32 s25, 0, 0x18000
	s_add_i32 s70, 0, 0x1c000
	v_add_u32_e32 v144, s25, v159
	v_add_u32_e32 v158, s70, v159
	ds_read_b128 v[132:135], v144
	ds_read_b128 v[136:139], v144 offset:1024
	ds_read_b128 v[140:143], v144 offset:2048
	ds_read_b128 v[144:147], v144 offset:3072
	ds_read_b128 v[190:193], v158
	ds_read_b128 v[194:197], v158 offset:1024
	ds_read_b128 v[198:201], v158 offset:2048
	ds_read_b128 v[202:205], v158 offset:3072
	s_add_u32 s40, s52, 0x40000
	s_addc_u32 s41, s53, 0
	s_mov_b32 m0, s58
	v_lshl_add_u64 v[184:185], s[40:41], 0, v[0:1]
	ds_read_b128 v[206:209], v179 offset:32768
	ds_read_b128 v[218:221], v179 offset:33792
	ds_read_b128 v[224:227], v179 offset:34816
	ds_read_b128 v[228:231], v179 offset:35840
	ds_read_b128 v[232:235], v179 offset:36864
	ds_read_b128 v[236:239], v179 offset:37888
	ds_read_b128 v[240:243], v179 offset:38912
	ds_read_b128 v[244:247], v179 offset:39936
	global_load_lds_dwordx4 v[184:185], off
	v_lshl_add_u64 v[184:185], s[40:41], 0, v[148:149]
	s_mov_b32 m0, s59
	s_nop 0
	global_load_lds_dwordx4 v[184:185], off
	s_waitcnt vmcnt(8)
	s_waitcnt lgkmcnt(0)
	s_barrier
	s_setprio 1
	s_waitcnt lgkmcnt(0)
	v_mfma_f32_16x16x32_bf16 v[128:131], v[132:135], v[206:209], v[128:131]
	v_mfma_f32_16x16x32_bf16 v[124:127], v[140:143], v[206:209], v[124:127]
	v_mfma_f32_16x16x32_bf16 v[112:115], v[132:135], v[224:227], v[112:115]
	v_mfma_f32_16x16x32_bf16 v[108:111], v[140:143], v[224:227], v[108:111]
	v_mfma_f32_16x16x32_bf16 v[96:99], v[132:135], v[232:235], v[96:99]
	v_mfma_f32_16x16x32_bf16 v[92:95], v[140:143], v[232:235], v[92:95]
	v_mfma_f32_16x16x32_bf16 v[80:83], v[132:135], v[240:243], v[80:83]
	v_mfma_f32_16x16x32_bf16 v[76:79], v[140:143], v[240:243], v[76:79]
	v_mfma_f32_16x16x32_bf16 v[128:131], v[136:139], v[218:221], v[128:131]
	v_mfma_f32_16x16x32_bf16 v[124:127], v[144:147], v[218:221], v[124:127]
	v_mfma_f32_16x16x32_bf16 v[112:115], v[136:139], v[228:231], v[112:115]
	v_mfma_f32_16x16x32_bf16 v[108:111], v[144:147], v[228:231], v[108:111]
	v_mfma_f32_16x16x32_bf16 v[96:99], v[136:139], v[236:239], v[96:99]
	v_mfma_f32_16x16x32_bf16 v[92:95], v[144:147], v[236:239], v[92:95]
	v_mfma_f32_16x16x32_bf16 v[80:83], v[136:139], v[244:247], v[80:83]
	v_mfma_f32_16x16x32_bf16 v[76:79], v[144:147], v[244:247], v[76:79]
	s_setprio 0
	s_setprio 1
	v_mfma_f32_16x16x32_bf16 v[120:123], v[190:193], v[206:209], v[120:123]
	v_mfma_f32_16x16x32_bf16 v[116:119], v[198:201], v[206:209], v[116:119]
	v_mfma_f32_16x16x32_bf16 v[104:107], v[190:193], v[224:227], v[104:107]
	v_mfma_f32_16x16x32_bf16 v[100:103], v[198:201], v[224:227], v[100:103]
	v_mfma_f32_16x16x32_bf16 v[88:91], v[190:193], v[232:235], v[88:91]
	v_mfma_f32_16x16x32_bf16 v[84:87], v[198:201], v[232:235], v[84:87]
	v_mfma_f32_16x16x32_bf16 v[72:75], v[190:193], v[240:243], v[72:75]
	v_mfma_f32_16x16x32_bf16 v[68:71], v[198:201], v[240:243], v[68:71]
	v_mfma_f32_16x16x32_bf16 v[120:123], v[194:197], v[218:221], v[120:123]
	v_mfma_f32_16x16x32_bf16 v[116:119], v[202:205], v[218:221], v[116:119]
	v_mfma_f32_16x16x32_bf16 v[104:107], v[194:197], v[228:231], v[104:107]
	v_mfma_f32_16x16x32_bf16 v[100:103], v[202:205], v[228:231], v[100:103]
	v_mfma_f32_16x16x32_bf16 v[88:91], v[194:197], v[236:239], v[88:91]
	v_mfma_f32_16x16x32_bf16 v[84:87], v[202:205], v[236:239], v[84:87]
	v_mfma_f32_16x16x32_bf16 v[72:75], v[194:197], v[244:247], v[72:75]
	v_mfma_f32_16x16x32_bf16 v[68:71], v[202:205], v[244:247], v[68:71]
	s_setprio 0
	s_barrier
	s_add_i32 s25, s25, s55
	v_lshl_add_u64 v[174:175], v[174:175], 0, s[94:95]
	s_mov_b32 m0, s25
	ds_read_b128 v[206:209], v179 offset:49152
	ds_read_b128 v[218:221], v179 offset:50176
	ds_read_b128 v[224:227], v179 offset:51200
	ds_read_b128 v[228:231], v179 offset:52224
	ds_read_b128 v[232:235], v179 offset:53248
	ds_read_b128 v[236:239], v179 offset:54272
	ds_read_b128 v[240:243], v179 offset:55296
	ds_read_b128 v[244:247], v179 offset:56320
	global_load_lds_dwordx4 v[174:175], off nt
	s_add_i32 m0, s25, 0x2000
	s_add_u32 s10, s10, 0x40080
	v_lshl_add_u64 v[174:175], v[210:211], 0, s[94:95]
	s_addc_u32 s11, s11, 0
	s_add_i32 s25, s70, s55
	global_load_lds_dwordx4 v[174:175], off nt
	v_lshl_add_u64 v[174:175], s[10:11], 0, v[180:181]
	s_mov_b32 m0, s25
	s_nop 0
	global_load_lds_dwordx4 v[174:175], off nt
	v_lshl_add_u64 v[174:175], s[10:11], 0, v[150:151]
	s_add_i32 m0, s25, 0x2000
	s_nop 0
	global_load_lds_dwordx4 v[174:175], off nt
	v_lshl_add_u64 v[174:175], v[248:249], 0, s[94:95]
	s_mov_b32 m0, s64
	s_nop 0
	global_load_lds_dwordx4 v[174:175], off
	v_lshl_add_u64 v[174:175], v[182:183], 0, s[94:95]
	s_mov_b32 m0, s65
	s_nop 0
	global_load_lds_dwordx4 v[174:175], off
	s_waitcnt vmcnt(8)
	s_waitcnt lgkmcnt(0)
	s_barrier
	s_setprio 1
	s_waitcnt lgkmcnt(0)
	v_mfma_f32_16x16x32_bf16 v[64:67], v[132:135], v[206:209], v[64:67]
	v_mfma_f32_16x16x32_bf16 v[60:63], v[140:143], v[206:209], v[60:63]
	v_mfma_f32_16x16x32_bf16 v[48:51], v[132:135], v[224:227], v[48:51]
	v_mfma_f32_16x16x32_bf16 v[44:47], v[140:143], v[224:227], v[44:47]
	v_mfma_f32_16x16x32_bf16 v[32:35], v[132:135], v[232:235], v[32:35]
	v_mfma_f32_16x16x32_bf16 v[28:31], v[140:143], v[232:235], v[28:31]
	v_mfma_f32_16x16x32_bf16 v[16:19], v[132:135], v[240:243], v[16:19]
	v_mfma_f32_16x16x32_bf16 v[12:15], v[140:143], v[240:243], v[12:15]
	v_mfma_f32_16x16x32_bf16 v[64:67], v[136:139], v[218:221], v[64:67]
	v_mfma_f32_16x16x32_bf16 v[60:63], v[144:147], v[218:221], v[60:63]
	v_mfma_f32_16x16x32_bf16 v[48:51], v[136:139], v[228:231], v[48:51]
	v_mfma_f32_16x16x32_bf16 v[44:47], v[144:147], v[228:231], v[44:47]
	v_mfma_f32_16x16x32_bf16 v[32:35], v[136:139], v[236:239], v[32:35]
	v_mfma_f32_16x16x32_bf16 v[28:31], v[144:147], v[236:239], v[28:31]
	v_mfma_f32_16x16x32_bf16 v[16:19], v[136:139], v[244:247], v[16:19]
	v_mfma_f32_16x16x32_bf16 v[12:15], v[144:147], v[244:247], v[12:15]
	s_setprio 0
	s_setprio 1
	v_mfma_f32_16x16x32_bf16 v[56:59], v[190:193], v[206:209], v[56:59]
	v_mfma_f32_16x16x32_bf16 v[52:55], v[198:201], v[206:209], v[52:55]
	v_mfma_f32_16x16x32_bf16 v[40:43], v[190:193], v[224:227], v[40:43]
	v_mfma_f32_16x16x32_bf16 v[36:39], v[198:201], v[224:227], v[36:39]
	v_mfma_f32_16x16x32_bf16 v[24:27], v[190:193], v[232:235], v[24:27]
	v_mfma_f32_16x16x32_bf16 v[20:23], v[198:201], v[232:235], v[20:23]
	v_mfma_f32_16x16x32_bf16 v[8:11], v[190:193], v[240:243], v[8:11]
	v_mfma_f32_16x16x32_bf16 v[4:7], v[198:201], v[240:243], v[4:7]
	v_mfma_f32_16x16x32_bf16 v[56:59], v[194:197], v[218:221], v[56:59]
	v_mfma_f32_16x16x32_bf16 v[52:55], v[202:205], v[218:221], v[52:55]
	v_mfma_f32_16x16x32_bf16 v[40:43], v[194:197], v[228:231], v[40:43]
	v_mfma_f32_16x16x32_bf16 v[36:39], v[202:205], v[228:231], v[36:39]
	v_mfma_f32_16x16x32_bf16 v[24:27], v[194:197], v[236:239], v[24:27]
	v_mfma_f32_16x16x32_bf16 v[20:23], v[202:205], v[236:239], v[20:23]
	v_mfma_f32_16x16x32_bf16 v[8:11], v[194:197], v[244:247], v[8:11]
	v_mfma_f32_16x16x32_bf16 v[4:7], v[202:205], v[244:247], v[4:7]
	s_setprio 0
	s_barrier
	s_add_i32 vcc_hi, vcc_hi, 2
	s_add_u32 s8, s8, 0x100
	s_addc_u32 s9, s9, 0
	s_add_u32 s97, s97, 0x100
	s_addc_u32 vcc_lo, vcc_lo, 0
	s_cmp_gt_u32 vcc_hi, 13
	s_cbranch_scc0 .LBB0_83
	s_and_b64 vcc, exec, s[16:17]
	s_cbranch_vccz .LBB0_86
	s_barrier
